# static priority: older co-resident block raised outside the attention loop, younger raised inside it
# speedup vs baseline: 1.0017x; 1.0005x over previous
; #define LAS __attribute__((address_space(3)))
; __device__ __forceinline__ unsigned xb_ld(unsigned* p)              { return __hip_atomic_load(p, __ATOMIC_RELAXED, __HIP_MEMORY_SCOPE_AGENT); }
; #define GSYNC() xcd_barrier(xb)
; __device__ __forceinline__ void xcd_barrier_complete(unsigned* bar, unsigned x, unsigned& nloc, unsigned& nx) {
;   const unsigned G = gridDim.x * gridDim.y * gridDim.z;
;   unsigned sum, cnt, mine, sp = 0u;
;   for (;;) {
;     sum = 0u; cnt = 0u; mine = 0u;
; #pragma unroll
;     for (unsigned j = 0; j < 16; ++j) { const unsigned c = xb_ld(&bar[XB_XCNT(j)]); sum += c; cnt += (c > 0u) ? 1u : 0u; mine = (j == x) ? c : mine; }
; __global__ void __launch_bounds__(NTHR, 2) mega(P p, int ph0, int ph1) {
;   extern __shared__ __attribute__((aligned(16))) char lds[];
;   if (ph1 < 0) cg::this_grid().sync();
;   volatile LAS unsigned* st = (volatile LAS unsigned*)(lds + LDS_BYTES);
;   if (threadIdx.x == 0) { st[0] = 0u; st[1] = 0u; st[2] = 0u; st[3] = 0u; }
;   __syncthreads();
;   const XcdBarrier xb = xcd_barrier_post((unsigned*)(p.ws + OFF_BAR), st);
;     ...
;   for (int i = 0; i < PROBE_SYNCS; ++i) GSYNC();
;   int ph = ph0;
.LBB0_143:
	v_readlane_b32 s4, v253, 0
	v_readlane_b32 s5, v253, 1
	s_add_u32 s4, s4, 0x118
	s_addc_u32 s5, s5, 0
	v_writelane_b32 v253, s4, 18
	s_lshl_b32 s3, s2, 8
	s_lshr_b32 s13, s2, 3
	s_and_b32 s98, s13, 32
	s_cmp_eq_u32 s98, 0
	s_cbranch_scc0 .Lgp_skip
	s_setprio 1
.Lgp_skip:
	v_writelane_b32 v253, s5, 19
	v_writelane_b32 v253, s3, 20
	s_and_b32 s3, s3, 0x700
	s_cmpk_lt_u32 s2, 0x800
	v_writelane_b32 v253, s3, 21
	s_cselect_b64 s[4:5], -1, 0
	v_writelane_b32 v253, s4, 22
	s_mov_b32 s93, 0
	s_mov_b32 s3, s93
	v_writelane_b32 v253, s5, 23
	s_and_b32 s4, s2, 7
	s_cmpk_lt_u32 s2, 0x2c00
	s_cselect_b64 s[6:7], -1, 0
	v_writelane_b32 v253, s6, 24
	v_mbcnt_lo_u32_b32 v0, -1, 0
	v_mov_b32_e32 v201, 0
	v_writelane_b32 v253, s7, 25
	s_lshl_b64 s[6:7], s[2:3], 8
	v_writelane_b32 v253, s6, 26
	s_cmpk_lt_u32 s2, 0x200
	v_mov_b32_e32 v215, 0xc0135761
	v_writelane_b32 v253, s7, 27
	s_cselect_b64 s[6:7], -1, 0
	v_writelane_b32 v253, s6, 28
	s_lshl_b32 s5, s2, 6
	s_and_b32 s58, s5, 0x1c0
	v_writelane_b32 v253, s7, 29
	s_ashr_i32 s6, s2, 3
	s_cmpk_lt_i32 s2, 0x400
	s_cselect_b64 s[8:9], -1, 0
	v_writelane_b32 v253, s8, 30
	s_cmpk_lt_i32 s2, 0x200
	v_mov_b32_e32 v182, 0x3727c5ac
	v_writelane_b32 v253, s9, 31
	s_cselect_b64 s[8:9], -1, 0
	v_writelane_b32 v253, s8, 32
	s_cmpk_lt_i32 s6, 0x80
	v_mbcnt_hi_u32_b32 v250, -1, v0
	v_writelane_b32 v253, s9, 33
	v_writelane_b32 v253, s6, 34
	s_cselect_b64 s[6:7], -1, 0
	v_writelane_b32 v253, s6, 35
	v_mov_b32_e32 v251, 0x42800000
	v_mov_b32_e32 v183, 0x42000000
	v_writelane_b32 v253, s7, 36
	v_writelane_b32 v253, s5, 37
	s_and_b32 s5, s5, 0x100
	v_writelane_b32 v253, s5, 38
	s_and_b32 s5, s2, 3
	s_lshl_b32 s6, s5, 7
	v_writelane_b32 v253, s6, 39
	s_lshl_b32 s6, s5, 1
	s_cmpk_lt_i32 s2, 0x100
	v_writelane_b32 v253, s6, 40
	s_cselect_b64 s[6:7], -1, 0
	v_writelane_b32 v253, s6, 41
	s_cmpk_lt_u32 s2, 0x1600
	v_not_b32_e32 v222, 63
	v_writelane_b32 v253, s7, 42
	s_cselect_b64 s[6:7], -1, 0
	v_writelane_b32 v253, s6, 43
	v_mov_b32_e32 v184, 0x7c000
	v_mov_b32_e32 v185, 0x2000
	v_writelane_b32 v253, s7, 44
	s_lshl_b64 s[6:7], s[2:3], 2
	v_writelane_b32 v253, s6, 45
	v_mov_b32_e32 v186, 0x7a000
	v_mov_b32_e32 v187, 0x4000
	v_writelane_b32 v253, s7, 46
	s_add_u32 s6, s0, 0x58c8300
	s_addc_u32 s7, s1, 0
	v_writelane_b32 v253, s6, 47
	v_mov_b32_e32 v188, 0x78000
	v_mov_b32_e32 v189, 0x6000
	v_writelane_b32 v253, s7, 48
	s_add_u32 s6, s0, 0x58c8500
	s_addc_u32 s7, s1, 0
	v_writelane_b32 v253, s6, 16
	v_mov_b32_e32 v190, 0x76000
	v_mov_b32_e32 v191, 0x8000
	v_writelane_b32 v253, s7, 17
	s_add_u32 s6, s0, 0x58c8600
	s_addc_u32 s7, s1, 0
	v_writelane_b32 v253, s6, 12
	v_mov_b32_e32 v192, 0x74000
	v_mov_b32_e32 v193, 0xa000
	v_writelane_b32 v253, s7, 13
	s_add_u32 s6, s0, 0x58c8700
	s_addc_u32 s7, s1, 0
	v_writelane_b32 v253, s6, 10
	v_mov_b32_e32 v194, 0x72000
	v_mov_b32_e32 v195, 0xc000
	v_writelane_b32 v253, s7, 11
	s_add_u32 s6, s0, 0x58c8800
	s_addc_u32 s7, s1, 0
	v_writelane_b32 v253, s6, 8
	v_mov_b32_e32 v196, 0x70000
	v_mov_b32_e32 v197, 0xe000
	v_writelane_b32 v253, s7, 9
	s_add_u32 s6, s0, 0x58c8900
	s_addc_u32 s7, s1, 0
	v_writelane_b32 v253, s6, 49
	v_mov_b32_e32 v198, 0x6e000
	v_mov_b32_e32 v199, 0x10000
	v_writelane_b32 v253, s7, 50
	s_add_u32 s6, s0, 0x58c8a00
	s_addc_u32 s7, s1, 0
	v_writelane_b32 v253, s6, 51
	v_mov_b32_e32 v202, 0x6c000
	v_mov_b32_e32 v203, 0x12000
	v_writelane_b32 v253, s7, 52
	s_add_u32 s6, s0, 0x58c8b00
	s_addc_u32 s7, s1, 0
	v_writelane_b32 v253, s6, 53
	v_mov_b32_e32 v204, 0x6a000
	v_mov_b32_e32 v206, 0x14000
	v_writelane_b32 v253, s7, 54
	s_add_u32 s6, s0, 0x58c8c00
	s_addc_u32 s7, s1, 0
	v_writelane_b32 v253, s6, 55
	v_mov_b32_e32 v207, 0x68000
	v_mov_b32_e32 v208, 0x16000
	v_writelane_b32 v253, s7, 56
	s_add_u32 s6, s0, 0x58c8d00
	s_addc_u32 s7, s1, 0
	v_writelane_b32 v253, s6, 57
	v_mov_b32_e32 v209, 0x66000
	v_mov_b32_e32 v210, 0x18000
	v_writelane_b32 v253, s7, 58
	s_add_u32 s6, s0, 0x58c8e00
	s_addc_u32 s7, s1, 0
	v_writelane_b32 v253, s6, 59
	v_mov_b32_e32 v211, 0x64000
	v_mov_b32_e32 v212, 0x1a000
	v_writelane_b32 v253, s7, 60
	s_add_u32 s6, s0, 0x58c8f00
	s_addc_u32 s7, s1, 0
	v_writelane_b32 v253, s6, 61
	v_mov_b32_e32 v213, 0x62000
	v_mov_b32_e32 v214, 0x1c000
	v_writelane_b32 v253, s7, 62
	s_add_u32 s6, s0, 0x58c9000
	s_addc_u32 s7, s1, 0
	v_writelane_b32 v253, s6, 63
	v_mov_b32_e32 v216, 0x60000
	v_readlane_b32 s8, v253, 6
	v_writelane_b32 v254, s7, 0
	s_add_u32 s6, s0, 0x58c9100
	s_addc_u32 s7, s1, 0
	v_writelane_b32 v254, s6, 1
	v_readlane_b32 s9, v253, 7
	v_mov_b32_e32 v218, 0x1e000
	v_writelane_b32 v254, s7, 2
	s_add_u32 s6, s0, 0x58c9200
	s_addc_u32 s7, s1, 0
	v_writelane_b32 v254, s6, 3
	v_mov_b32_e32 v219, 0x5e000
	v_mov_b32_e32 v220, 0x20000
	v_writelane_b32 v254, s7, 4
	s_add_u32 s6, s0, 0x58c9300
	s_addc_u32 s7, s1, 0
	v_writelane_b32 v254, s6, 5
	v_mov_b32_e32 v221, 0x5c000
	v_mov_b32_e32 v228, 0x22000
; __device__ __forceinline__ unsigned xb_ld(unsigned* p)              { return __hip_atomic_load(p, __ATOMIC_RELAXED, __HIP_MEMORY_SCOPE_AGENT); }
; __device__ __forceinline__ void xcd_barrier_complete(unsigned* bar, unsigned x, unsigned& nloc, unsigned& nx) {
;   const unsigned G = gridDim.x * gridDim.y * gridDim.z;
;   unsigned sum, cnt, mine, sp = 0u;
;   for (;;) {
;     sum = 0u; cnt = 0u; mine = 0u;
; #pragma unroll
;     for (unsigned j = 0; j < 16; ++j) { const unsigned c = xb_ld(&bar[XB_XCNT(j)]); sum += c; cnt += (c > 0u) ? 1u : 0u; mine = (j == x) ? c : mine; }
;     if (sum == G) break;
;     __builtin_amdgcn_s_sleep(1);
;     if ((++sp & 255u) == 0u) { if (xb_ld(&bar[XB_TMO])) break; if (sp > XB_SPIN_CAP) { atomicAdd(&bar[XB_TMO], 1u); break; } }
;   }
;   nloc = mine > 0u ? mine : 1u; nx = cnt > 0u ? cnt : 1u;
; }
	v_writelane_b32 v254, s7, 6
	s_add_u32 s6, s0, 0x58c9400
	s_addc_u32 s7, s1, 0
	v_writelane_b32 v254, s6, 7
	s_cmp_eq_u32 s33, 15
	v_mov_b32_e32 v230, 0x5a000
	v_writelane_b32 v254, s7, 8
	s_cselect_b64 s[6:7], -1, 0
	v_writelane_b32 v254, s6, 9
	s_cmp_eq_u32 s33, 14
	v_mov_b32_e32 v231, 0x24000
	v_writelane_b32 v254, s7, 10
	s_cselect_b64 s[6:7], -1, 0
	v_writelane_b32 v254, s6, 11
	s_cmp_eq_u32 s33, 13
	v_mov_b32_e32 v232, 0x58000
	v_writelane_b32 v254, s7, 12
	s_cselect_b64 s[6:7], -1, 0
	v_writelane_b32 v254, s6, 13
	s_cmp_eq_u32 s33, 12
	v_mov_b32_e32 v233, 0x26000
	v_writelane_b32 v254, s7, 14
	s_cselect_b64 s[6:7], -1, 0
	v_writelane_b32 v254, s6, 15
	s_cmp_eq_u32 s33, 11
	v_mov_b32_e32 v234, 0x56000
	v_writelane_b32 v254, s7, 16
	s_cselect_b64 s[6:7], -1, 0
	v_writelane_b32 v254, s6, 17
	s_cmp_eq_u32 s33, 10
	v_mov_b32_e32 v235, 0x28000
	v_writelane_b32 v254, s7, 18
	s_cselect_b64 s[6:7], -1, 0
	v_writelane_b32 v254, s6, 19
	s_cmp_eq_u32 s33, 9
	v_mov_b32_e32 v236, 0x54000
	v_writelane_b32 v254, s7, 20
	s_cselect_b64 s[6:7], -1, 0
	v_writelane_b32 v254, s6, 21
	s_cmp_eq_u32 s33, 8
	v_mov_b32_e32 v237, 0x2a000
	v_writelane_b32 v254, s7, 22
	s_cselect_b64 s[6:7], -1, 0
	v_writelane_b32 v254, s6, 23
	s_cmp_eq_u32 s33, 7
	v_mov_b32_e32 v238, 0x52000
	v_writelane_b32 v254, s7, 24
	s_cselect_b64 s[6:7], -1, 0
	v_writelane_b32 v254, s6, 25
	s_cmp_eq_u32 s33, 6
	v_mov_b32_e32 v239, 0x2c000
	v_writelane_b32 v254, s7, 26
	s_cselect_b64 s[6:7], -1, 0
	v_writelane_b32 v254, s6, 27
	s_cmp_eq_u32 s33, 5
	v_mov_b32_e32 v240, 0x50000
	v_writelane_b32 v254, s7, 28
	s_cselect_b64 s[6:7], -1, 0
	v_writelane_b32 v254, s6, 29
	s_cmp_eq_u32 s33, 4
	v_mov_b32_e32 v241, 0x2e000
	v_writelane_b32 v254, s7, 30
	s_cselect_b64 s[6:7], -1, 0
	v_writelane_b32 v254, s6, 31
	s_cmp_eq_u32 s33, 3
	v_mov_b32_e32 v242, 0x4e000
	v_writelane_b32 v254, s7, 32
	s_cselect_b64 s[6:7], -1, 0
	v_writelane_b32 v254, s6, 33
	s_cmp_eq_u32 s33, 2
	v_mov_b32_e32 v243, 0x30000
	v_writelane_b32 v254, s7, 34
	s_cselect_b64 s[6:7], -1, 0
	v_writelane_b32 v254, s6, 35
	s_cmp_eq_u32 s33, 1
	v_mov_b32_e32 v244, 0x4c000
	v_writelane_b32 v254, s7, 36
	s_cselect_b64 s[6:7], -1, 0
	v_writelane_b32 v254, s6, 37
	s_cmp_eq_u32 s33, 0
	v_mov_b32_e32 v245, 0x32000
	v_writelane_b32 v254, s7, 38
	s_cselect_b64 s[6:7], -1, 0
	v_writelane_b32 v254, s6, 39
	v_mov_b32_e32 v246, 0x4a000
	v_mov_b32_e32 v247, 0x34000
	v_writelane_b32 v254, s7, 40
	s_lshl_b32 s6, s33, 8
	s_add_u32 s6, s8, s6
	s_addc_u32 s7, s9, 0
	s_add_u32 s8, s6, 0x1400
	s_addc_u32 s9, s7, 0
	v_writelane_b32 v254, s8, 41
	s_add_u32 s6, s6, 0x2400
	s_addc_u32 s7, s7, 0
	v_writelane_b32 v254, s9, 42
	v_writelane_b32 v254, s6, 43
	v_mov_b32_e32 v248, 0x48000
	v_mov_b32_e32 v249, 0x36000
	v_writelane_b32 v254, s7, 44
	s_add_u32 s6, s0, 0x58cb500
	s_addc_u32 s7, s1, 0
	v_writelane_b32 v254, s6, 45
	s_add_u32 s0, s0, 0x58cb600
	s_addc_u32 s1, s1, 0
	v_writelane_b32 v254, s7, 46
	v_writelane_b32 v254, s0, 47
	v_mov_b32_e32 v179, 0x46000
	v_mov_b32_e32 v181, 0x38000
	v_writelane_b32 v254, s1, 48
	s_lshl_b64 s[0:1], s[2:3], 12
	s_add_u32 s0, s0, 0x190cff00
	v_writelane_b32 v254, s0, 49
	s_addc_u32 s0, s1, 0
	v_writelane_b32 v254, s0, 50
	s_lshl_b64 s[0:1], s[2:3], 13
	s_or_b32 s6, s0, 16
	v_writelane_b32 v254, s6, 51
	s_mov_b32 s6, s1
	v_writelane_b32 v254, s6, 52
	s_add_u32 s0, s0, 0x60d0300
	v_writelane_b32 v254, s0, 53
	s_addc_u32 s0, s1, 0
	v_writelane_b32 v254, s0, 54
	s_mul_i32 s0, s4, 0x580
	v_writelane_b32 v254, s0, 55
	s_mul_i32 s0, s4, 0x2c0
	v_writelane_b32 v253, s0, 6
	s_lshl_b32 s0, s5, 8
	v_writelane_b32 v254, s0, 56
	s_lshl_b32 s0, s2, 7
	v_writelane_b32 v254, s0, 57
	s_lshl_b32 s0, s2, 5
	v_writelane_b32 v254, s0, 58
	s_lshl_b32 s0, s2, 9
	v_writelane_b32 v254, s0, 59
	s_lshl_b32 s0, s2, 10
	v_writelane_b32 v254, s0, 60
	s_add_i32 s0, 0, 0x12400
	v_writelane_b32 v254, s0, 61
	s_add_i32 s0, 0, 0x12404
	v_writelane_b32 v254, s0, 62
	s_lshl_b64 s[0:1], s[2:3], 14
	v_writelane_b32 v254, s0, 63
	s_mov_b64 s[4:5], 0x380
	s_movk_i32 s9, 0x1600
	v_writelane_b32 v255, s1, 0
	v_writelane_b32 v255, s4, 1
	s_movk_i32 s10, 0x1000
	s_mov_b32 s94, 0x1ffffc0
	v_writelane_b32 v255, s5, 2
	v_writelane_b32 v255, s6, 3
	v_writelane_b32 v255, s7, 4
	s_mov_b32 s12, 0x3fb504f3
	s_movk_i32 s11, 0xb00
	s_mov_b32 s14, 0x800000
	s_mov_b32 s15, 0xc2fc0000
	s_movk_i32 s16, 0x2ff
	s_movk_i32 s95, 0x90
	s_mov_b32 s17, 0x5540000
	s_mov_b64 s[28:29], 0x1400
	s_mov_b64 s[78:79], 0x80
	s_mov_b64 s[24:25], 0x100
	s_mov_b64 s[74:75], 0x180
	s_mov_b64 s[20:21], 0x200
	s_mov_b64 s[86:87], 0x280
	s_mov_b64 s[30:31], 0x300
	s_mov_b64 s[66:67], 0x400
	s_mov_b64 s[26:27], 0x480
	s_mov_b64 s[88:89], 0x500
	s_mov_b64 s[22:23], 0x580
	s_mov_b64 s[90:91], 0x600
	s_mov_b64 s[0:1], 0x680
	s_mov_b64 s[34:35], 0x700
	s_mov_b64 s[38:39], 0x780
	s_mov_b64 s[36:37], 0x8000
	v_writelane_b32 v255, s58, 5
	s_branch .LBB0_147

; __device__ __forceinline__ void attn_item(const P& p, int layer, int item, char* lds) {
;     ...
;   const float lam = ((const float*)(p.ws + OFF_LAM))[layer];
;   const u16* Kg = z + tokb * ZC + C_DAK + h * 128; const u16* Vg = z + tokb * ZC + C_DAV + h * 128;
;   bf16x8 q1[4], q2[2];
;   char* Qp = lds + 2 * STG + 1024 + tid * 16;
; #pragma unroll
;   for (int d0 = 0; d0 < 4; ++d0) q1[d0] = *(const bf16x8*)(z + (tokq + wid * 32 + r32) * ZC + h * 128 + d0 * 16 + hi * 8);
; #pragma unroll
;   for (int d0 = 0; d0 < 2; ++d0) q2[d0] = *(const bf16x8*)(z + (tokq + wid * 32 + r32) * ZC + h * 128 + 64 + d0 * 16 + hi * 8);
;   __syncthreads();
;   float qs1 = 0.f, qs2 = 0.f;
; #pragma unroll
;   for (int d0 = 0; d0 < 4; ++d0) qs1 += sumsq8(q1[d0]);
; #pragma unroll
;   for (int d0 = 0; d0 < 2; ++d0) qs2 += sumsq8(q2[d0]);
; #pragma unroll
;   for (int d0 = 2; d0 < 4; ++d0) { const bf16x8 t = *(const bf16x8*)(z + (tokq + wid * 32 + r32) * ZC + h * 128 + 64 + d0 * 16 + hi * 8);
;     qs2 += sumsq8(t); *(bf16x8*)(Qp + (d0 - 2) * 4096) = t; }
.LBB0_271:
	s_lshl_b32 s3, s83, 3
	s_and_b32 s3, s3, 0xfffffe00
	v_readlane_b32 s6, v253, 38
	s_or_b32 s8, s3, s6
	v_mov_b32_e32 v214, v229
	s_ashr_i32 s6, s8, 8
	s_ashr_i32 s7, s6, 31
	s_lshl_b32 s3, s83, 7
	s_waitcnt vmcnt(7)
	v_ashrrev_i32_e32 v0, 1, v214
	s_lshl_b64 s[70:71], s[6:7], 13
	s_and_b32 s3, s3, 0x1f80
	v_and_b32_e32 v202, 0xffffffe0, v0
	s_or_b32 s70, s70, s3
	v_ashrrev_i32_e32 v203, 31, v202
	v_and_b32_e32 v226, 31, v214
	v_lshl_add_u64 v[0:1], s[70:71], 0, v[202:203]
	v_or_b32_e32 v0, v0, v226
	v_mov_b64_e32 v[2:3], s[58:59]
	v_bfe_u32 v227, v214, 5, 1
	v_mad_u64_u32 v[2:3], s[18:19], v0, s9, v[2:3]
	v_mad_i32_i24 v3, v1, s9, v3
	v_lshlrev_b32_e32 v200, 4, v227
	v_lshl_add_u64 v[0:1], v[2:3], 0, v[200:201]
	global_load_dwordx4 v[180:183], v[0:1], off
	global_load_dwordx4 v[176:179], v[0:1], off offset:32
	global_load_dwordx4 v[172:175], v[0:1], off offset:64
	global_load_dword v225, v201, s[42:43]
	global_load_dwordx4 v[168:171], v[0:1], off offset:96
	global_load_dwordx4 v[164:167], v[0:1], off offset:128
	global_load_dwordx4 v[160:163], v[0:1], off offset:160
	v_lshlrev_b32_e32 v2, 1, v214
	s_waitcnt vmcnt(13)
	v_lshrrev_b32_e32 v4, 4, v214
	v_lshrrev_b32_e32 v3, 3, v214
	v_bfe_u32 v6, v214, 2, 3
	s_waitcnt vmcnt(12)
	v_ashrrev_i32_e32 v8, 4, v214
	v_and_b32_e32 v11, 32, v2
	v_xor_b32_e32 v2, v4, v214
	s_mov_b32 s3, 0xfffff8
	s_movk_i32 s33, 0xb00
	v_and_or_b32 v4, v8, s3, v6
	v_mul_lo_u32 v3, v3, s33
	s_waitcnt vmcnt(11)
	v_lshlrev_b32_e32 v14, 3, v2
	v_mul_u32_u24_e32 v2, 0xb00, v4
	v_and_or_b32 v4, v14, 56, v3
	s_barrier
	global_load_dwordx4 v[14:17], v[0:1], off offset:192
	s_mul_i32 s7, s6, 0x2c00000
	s_mul_hi_i32 s3, s6, 0x2c00000
	s_add_u32 s76, s58, s7
	s_addc_u32 s77, s59, s3
	s_ashr_i32 s6, s8, 5
	v_readlane_b32 s8, v253, 40
	s_or_b32 s18, s6, s8
	s_ashr_i32 s19, s18, 31
	s_lshl_b64 s[18:19], s[18:19], 9
	v_and_b32_e32 v228, 63, v214
	s_add_u32 s18, s73, s18
	s_addc_u32 s19, s80, s19
	v_lshlrev_b32_e32 v5, 4, v214
	v_and_b32_e32 v13, 0xc0, v5
	v_add_u32_e32 v232, 0, v5
	v_add_u32_e32 v230, 0x10400, v232
	s_mov_b32 s52, 0xf800000
	v_readfirstlane_b32 s8, v232
	s_mov_b32 m0, s8
	v_lshlrev_b32_e32 v10, 3, v214
	v_and_b32_e32 v7, 0x60, v214
	v_and_b32_e32 v12, 24, v10
	v_or3_b32 v2, v2, v7, v12
	s_cmp_lg_u32 0, -1
	v_lshrrev_b32_e32 v9, 1, v214
	s_mov_b32 s6, 0
	v_lshl_add_u32 v236, v226, 7, 0
	s_movk_i32 s11, 0xb00
	s_waitcnt vmcnt(7)
	v_and_b32_e32 v18, 0xffff0000, v180
	s_waitcnt vmcnt(6)
	v_and_b32_e32 v26, 0xffff0000, v176
	v_lshlrev_b32_e32 v3, 16, v180
	v_lshlrev_b32_e32 v25, 16, v176
	v_mul_f32_e32 v18, v18, v18
	v_mul_f32_e32 v26, v26, v26
	v_lshlrev_b32_e32 v19, 16, v181
	v_lshlrev_b32_e32 v27, 16, v177
	v_fmac_f32_e32 v18, v3, v3
	v_fmac_f32_e32 v26, v25, v25
	v_and_b32_e32 v20, 0xffff0000, v181
	v_and_b32_e32 v28, 0xffff0000, v177
	v_fmac_f32_e32 v18, v19, v19
	v_fmac_f32_e32 v26, v27, v27
	v_lshlrev_b32_e32 v21, 16, v182
	v_lshlrev_b32_e32 v29, 16, v178
	s_waitcnt vmcnt(5)
	v_and_b32_e32 v34, 0xffff0000, v172
	v_fmac_f32_e32 v18, v20, v20
	v_fmac_f32_e32 v26, v28, v28
	v_and_b32_e32 v22, 0xffff0000, v182
	v_and_b32_e32 v30, 0xffff0000, v178
	v_lshlrev_b32_e32 v33, 16, v172
	v_mul_f32_e32 v34, v34, v34
	v_fmac_f32_e32 v18, v21, v21
	v_fmac_f32_e32 v26, v29, v29
	v_lshlrev_b32_e32 v23, 16, v183
	v_lshlrev_b32_e32 v31, 16, v179
	v_lshlrev_b32_e32 v35, 16, v173
	v_fmac_f32_e32 v34, v33, v33
	v_fmac_f32_e32 v18, v22, v22
	v_fmac_f32_e32 v26, v30, v30
	v_and_b32_e32 v24, 0xffff0000, v183
	v_and_b32_e32 v32, 0xffff0000, v179
	v_and_b32_e32 v36, 0xffff0000, v173
	v_fmac_f32_e32 v34, v35, v35
	v_fmac_f32_e32 v18, v23, v23
	v_fmac_f32_e32 v26, v31, v31
	v_lshlrev_b32_e32 v37, 16, v174
	v_fmac_f32_e32 v34, v36, v36
	v_fmac_f32_e32 v18, v24, v24
	v_fmac_f32_e32 v26, v32, v32
	v_fmac_f32_e32 v34, v37, v37
	v_add_f32_e32 v3, v18, v26
	v_and_b32_e32 v18, 0xffff0000, v174
	v_fmac_f32_e32 v34, v18, v18
	v_lshlrev_b32_e32 v18, 16, v175
	v_fmac_f32_e32 v34, v18, v18
	v_and_b32_e32 v18, 0xffff0000, v175
	v_fmac_f32_e32 v34, v18, v18
	s_waitcnt vmcnt(3)
	v_and_b32_e32 v23, 0xffff0000, v168
	global_load_dwordx4 v[18:21], v[0:1], off offset:224
	v_lshlrev_b32_e32 v1, 2, v228
	v_mul_f32_e32 v0, v23, v23
	global_load_dword v23, v1, s[18:19] offset:256
	global_load_dword v24, v1, s[18:19] offset:512
	global_load_dword v25, v1, s[18:19] offset:768
	s_nop 0
	global_load_dword v1, v1, s[18:19]
	v_lshlrev_b32_e32 v22, 16, v168
	v_fmac_f32_e32 v0, v22, v22
	v_lshlrev_b32_e32 v22, 16, v169
	v_fmac_f32_e32 v0, v22, v22
	v_and_b32_e32 v22, 0xffff0000, v169
	v_fmac_f32_e32 v0, v22, v22
	v_lshlrev_b32_e32 v22, 16, v170
	v_fmac_f32_e32 v0, v22, v22
	v_and_b32_e32 v22, 0xffff0000, v170
	v_fmac_f32_e32 v0, v22, v22
	v_lshlrev_b32_e32 v22, 16, v171
	v_fmac_f32_e32 v0, v22, v22
	v_and_b32_e32 v22, 0xffff0000, v171
	v_add_f32_e32 v3, v3, v34
	v_fmac_f32_e32 v0, v22, v22
	s_waitcnt vmcnt(7)
	v_and_b32_e32 v5, 0xffff0000, v164
	v_add_f32_e32 v0, v3, v0
	v_lshlrev_b32_e32 v3, 16, v164
	v_mul_f32_e32 v5, v5, v5
	v_fmac_f32_e32 v5, v3, v3
	v_lshlrev_b32_e32 v3, 16, v165
	v_fmac_f32_e32 v5, v3, v3
	v_and_b32_e32 v3, 0xffff0000, v165
	v_fmac_f32_e32 v5, v3, v3
	v_lshlrev_b32_e32 v3, 16, v166
	v_fmac_f32_e32 v5, v3, v3
	v_and_b32_e32 v3, 0xffff0000, v166
	v_fmac_f32_e32 v5, v3, v3
	v_lshlrev_b32_e32 v3, 16, v167
	v_fmac_f32_e32 v5, v3, v3
	v_and_b32_e32 v3, 0xffff0000, v167
	s_waitcnt vmcnt(6)
; __device__ __forceinline__ void attn_item(const P& p, int layer, int item, char* lds) {
;     ...
;   float qs1 = 0.f, qs2 = 0.f;
; #pragma unroll
;   for (int d0 = 0; d0 < 4; ++d0) qs1 += sumsq8(q1[d0]);
; #pragma unroll
;   for (int d0 = 0; d0 < 2; ++d0) qs2 += sumsq8(q2[d0]);
; #pragma unroll
;   for (int d0 = 2; d0 < 4; ++d0) { const bf16x8 t = *(const bf16x8*)(z + (tokq + wid * 32 + r32) * ZC + h * 128 + 64 + d0 * 16 + hi * 8);
;     qs2 += sumsq8(t); *(bf16x8*)(Qp + (d0 - 2) * 4096) = t; }
;   { auto rr = __builtin_amdgcn_permlane32_swap(__float_as_uint(qs1), __float_as_uint(qs1), false, false); qs1 = __uint_as_float(rr[0]) + __uint_as_float(rr[1]); }
;   { auto rr = __builtin_amdgcn_permlane32_swap(__float_as_uint(qs2), __float_as_uint(qs2), false, false); qs2 = __uint_as_float(rr[0]) + __uint_as_float(rr[1]); }
;   float mC1, mC2;
;   { const float* kmx = (const float*)(p.ws + OFF_KMX) + (size_t)((b * 4 + h) * 2) * 128;
;     float k1 = fmaxf(kmx[lane], kmx[64 + lane]), k2 = fmaxf(kmx[128 + lane], kmx[192 + lane]);
; #pragma unroll
;     for (int o = 32; o >= 1; o >>= 1) { k1 = fmaxf(k1, __shfl_xor(k1, o)); k2 = fmaxf(k2, __shfl_xor(k2, o)); }
;     mC1 = sqrtf(qs1 * k1) * 1.4426950408889634f; mC2 = sqrtf(qs2 * k2) * 1.4426950408889634f; }
;   float l1 = 0.f, l2 = 0.f;
;   f32x16 o1[4], o2[4];
; #pragma unroll
;   for (int d = 0; d < 4; ++d) { o1[d] = f32x16{}; o2[d] = f32x16{}; }
;     ...
;   __syncthreads();
;   ISSUE_T(0, 0);
	v_and_b32_e32 v22, 0xffff0000, v160
	v_fmac_f32_e32 v5, v3, v3
	v_lshlrev_b32_e32 v3, 16, v160
	v_mul_f32_e32 v22, v22, v22
	v_fmac_f32_e32 v22, v3, v3
	v_lshlrev_b32_e32 v3, 16, v161
	v_fmac_f32_e32 v22, v3, v3
	v_and_b32_e32 v3, 0xffff0000, v161
	v_fmac_f32_e32 v22, v3, v3
	v_lshlrev_b32_e32 v3, 16, v162
	v_fmac_f32_e32 v22, v3, v3
	v_and_b32_e32 v3, 0xffff0000, v162
	v_fmac_f32_e32 v22, v3, v3
	v_lshlrev_b32_e32 v3, 16, v163
	v_fmac_f32_e32 v22, v3, v3
	v_and_b32_e32 v3, 0xffff0000, v163
	v_fmac_f32_e32 v22, v3, v3
	v_add_f32_e32 v3, v5, v22
	s_waitcnt vmcnt(5)
	v_and_b32_e32 v22, 0xffff0000, v14
	v_lshlrev_b32_e32 v5, 16, v14
	v_mul_f32_e32 v22, v22, v22
	v_fmac_f32_e32 v22, v5, v5
	v_lshlrev_b32_e32 v5, 16, v15
	v_fmac_f32_e32 v22, v5, v5
	v_and_b32_e32 v5, 0xffff0000, v15
	v_fmac_f32_e32 v22, v5, v5
	v_lshlrev_b32_e32 v5, 16, v16
	v_fmac_f32_e32 v22, v5, v5
	v_and_b32_e32 v5, 0xffff0000, v16
	v_fmac_f32_e32 v22, v5, v5
	v_lshlrev_b32_e32 v5, 16, v17
	v_fmac_f32_e32 v22, v5, v5
	v_and_b32_e32 v5, 0xffff0000, v17
	v_fmac_f32_e32 v22, v5, v5
	ds_write_b128 v230, v[14:17]
	v_and_b32_e32 v17, 64, v250
	v_add_f32_e32 v3, v3, v22
	v_add_u32_e32 v17, 64, v17
	v_xor_b32_e32 v22, 32, v250
	v_cmp_lt_i32_e32 vcc, v22, v17
	s_mov_b64 s[18:19], 0x2c400
	s_waitcnt vmcnt(3)
	v_max_f32_e32 v15, v23, v23
	v_cndmask_b32_e32 v22, v250, v22, vcc
	v_lshlrev_b32_e32 v22, 2, v22
	s_waitcnt vmcnt(0)
	v_max_f32_e32 v1, v1, v1
	v_max_f32_e32 v1, v1, v15
	ds_bpermute_b32 v23, v22, v1
	v_max_f32_e32 v15, v25, v25
	v_max_f32_e32 v16, v24, v24
	v_max_f32_e32 v15, v16, v15
	ds_bpermute_b32 v16, v22, v15
	s_waitcnt lgkmcnt(1)
	v_max_f32_e32 v22, v23, v23
	v_max_f32_e32 v1, v1, v22
	v_xor_b32_e32 v22, 16, v250
	v_cmp_lt_i32_e32 vcc, v22, v17
	s_waitcnt lgkmcnt(0)
	v_max_f32_e32 v16, v16, v16
	v_max_f32_e32 v15, v15, v16
	v_cndmask_b32_e32 v22, v250, v22, vcc
	v_lshlrev_b32_e32 v203, 2, v22
	ds_bpermute_b32 v22, v203, v1
	v_and_b32_e32 v14, 0xffff0000, v18
	ds_bpermute_b32 v16, v203, v15
	v_lshlrev_b32_e32 v5, 16, v18
	v_mul_f32_e32 v14, v14, v14
	s_waitcnt lgkmcnt(1)
	v_max_f32_e32 v22, v22, v22
	v_fmac_f32_e32 v14, v5, v5
	v_lshlrev_b32_e32 v5, 16, v19
	v_max_f32_e32 v1, v1, v22
	v_xor_b32_e32 v22, 8, v250
	v_fmac_f32_e32 v14, v5, v5
	v_and_b32_e32 v5, 0xffff0000, v19
	v_cmp_lt_i32_e32 vcc, v22, v17
	v_fmac_f32_e32 v14, v5, v5
	v_lshlrev_b32_e32 v5, 16, v20
	v_cndmask_b32_e32 v22, v250, v22, vcc
	v_fmac_f32_e32 v14, v5, v5
	v_and_b32_e32 v5, 0xffff0000, v20
	s_waitcnt lgkmcnt(0)
	v_max_f32_e32 v16, v16, v16
	v_lshlrev_b32_e32 v252, 2, v22
	v_fmac_f32_e32 v14, v5, v5
	v_lshlrev_b32_e32 v5, 16, v21
	ds_bpermute_b32 v22, v252, v1
	v_max_f32_e32 v15, v15, v16
	v_fmac_f32_e32 v14, v5, v5
	v_and_b32_e32 v5, 0xffff0000, v21
	ds_bpermute_b32 v16, v252, v15
	v_fmac_f32_e32 v14, v5, v5
	v_add_f32_e32 v3, v3, v14
	v_xor_b32_e32 v14, 4, v250
	v_cmp_lt_i32_e32 vcc, v14, v17
	s_waitcnt lgkmcnt(1)
	v_max_f32_e32 v5, v22, v22
	v_max_f32_e32 v1, v1, v5
	v_cndmask_b32_e32 v14, v250, v14, vcc
	s_waitcnt lgkmcnt(0)
	v_max_f32_e32 v5, v16, v16
	v_lshlrev_b32_e32 v217, 2, v14
	ds_bpermute_b32 v14, v217, v1
	v_max_f32_e32 v5, v15, v5
	ds_bpermute_b32 v15, v217, v5
	v_mov_b32_e32 v16, v0
	s_nop 1
	v_permlane32_swap_b32_e32 v0, v16
	s_waitcnt lgkmcnt(1)
	v_max_f32_e32 v14, v14, v14
	v_max_f32_e32 v1, v1, v14
	s_waitcnt lgkmcnt(0)
	v_max_f32_e32 v14, v15, v15
	v_max_f32_e32 v5, v5, v14
	v_xor_b32_e32 v14, 2, v250
	v_cmp_lt_i32_e32 vcc, v14, v17
	v_add_f32_e32 v0, v0, v16
	ds_write_b128 v230, v[18:21] offset:4096
	v_cndmask_b32_e32 v14, v250, v14, vcc
	v_lshlrev_b32_e32 v223, 2, v14
	ds_bpermute_b32 v14, v223, v1
	ds_bpermute_b32 v15, v223, v5
	v_mov_b32_e32 v18, v3
	s_nop 1
	v_permlane32_swap_b32_e32 v3, v18
	s_waitcnt lgkmcnt(1)
	v_max_f32_e32 v14, v14, v14
	v_max_f32_e32 v1, v1, v14
	s_waitcnt lgkmcnt(0)
	v_max_f32_e32 v14, v15, v15
	v_max_f32_e32 v5, v5, v14
	v_xor_b32_e32 v14, 1, v250
	v_cmp_lt_i32_e32 vcc, v14, v17
	v_add_f32_e32 v3, v3, v18
	v_mov_b32_e32 v21, 0x260
	v_cndmask_b32_e32 v14, v250, v14, vcc
	v_lshlrev_b32_e32 v224, 2, v14
	ds_bpermute_b32 v14, v224, v1
	ds_bpermute_b32 v15, v224, v5
	s_waitcnt lgkmcnt(0)
	s_barrier
	v_max_f32_e32 v14, v14, v14
	v_max_f32_e32 v1, v1, v14
	v_mul_f32_e32 v0, v0, v1
	v_mul_f32_e32 v1, 0x4f800000, v0
	v_cmp_gt_f32_e32 vcc, s52, v0
	v_max_f32_e32 v14, v15, v15
	s_nop 0
	v_cndmask_b32_e32 v1, v0, v1, vcc
	v_sqrt_f32_e32 v15, v1
	v_max_f32_e32 v0, v5, v14
	v_mul_f32_e32 v20, v3, v0
	v_mov_b32_e32 v0, 0
	v_add_u32_e32 v3, -1, v15
	v_fma_f32 v5, -v3, v15, v1
	v_cmp_ge_f32_e64 s[40:41], 0, v5
	v_add_u32_e32 v5, 1, v15
	v_fma_f32 v14, -v5, v15, v1
	v_cndmask_b32_e64 v3, v15, v3, s[40:41]
	v_cmp_lt_f32_e64 s[40:41], 0, v14
	v_mov_b32_e32 v22, v0
	v_mov_b32_e32 v23, v0
	v_cndmask_b32_e64 v3, v3, v5, s[40:41]
	v_mul_f32_e32 v5, 0x37800000, v3
	v_cndmask_b32_e32 v3, v3, v5, vcc
	v_mov_b32_e32 v5, v201
	v_cmp_class_f32_e32 vcc, v1, v21
	v_lshlrev_b64 v[4:5], 1, v[4:5]
	v_lshl_add_u64 v[14:15], s[76:77], 0, v[4:5]
	v_cndmask_b32_e32 v1, v3, v1, vcc
	v_add_u32_e32 v3, 0x2000, v232
	v_lshl_add_u64 v[16:17], v[14:15], 0, s[66:67]
	v_readfirstlane_b32 s8, v3
	v_add_u32_e32 v3, 0x1000, v232
	v_lshl_add_u64 v[18:19], v[14:15], 0, s[26:27]
	global_load_lds_dwordx4 v[16:17], off
	s_mov_b32 m0, s8
	v_readfirstlane_b32 s8, v3
	global_load_lds_dwordx4 v[18:19], off
	v_lshl_add_u64 v[16:17], v[14:15], 0, s[18:19]
	s_mov_b32 m0, s8
	v_add_u32_e32 v3, 0x3000, v232
	global_load_lds_dwordx4 v[16:17], off
	s_mov_b64 s[18:19], 0x2c480
	v_readfirstlane_b32 s8, v3
	v_mov_b32_e32 v3, v201
	v_add_u32_e32 v17, 0x4000, v232
	v_lshl_add_u64 v[14:15], v[14:15], 0, s[18:19]
; __device__ __forceinline__ void attn_item(const P& p, int layer, int item, char* lds) {
;     ...
;   float l1 = 0.f, l2 = 0.f;
;   f32x16 o1[4], o2[4];
; #pragma unroll
;   for (int d = 0; d < 4; ++d) { o1[d] = f32x16{}; o2[d] = f32x16{}; }
;     ...
;   __syncthreads();
;   ISSUE_T(0, 0);
;   for (int j = 0; j < NTILE; ++j) {
;     asm volatile("s_waitcnt vmcnt(0)" ::: "memory"); __syncthreads();
;     if (j + 1 < NTILE) ISSUE_T(j + 1, (j + 1) & 1);
	s_mov_b32 m0, s8
	v_lshl_add_u64 v[2:3], v[2:3], 1, s[76:77]
	s_mov_b64 s[18:19], 0x800
	v_readfirstlane_b32 s8, v17
	v_add_u32_e32 v17, 0x5000, v232
	global_load_lds_dwordx4 v[14:15], off
	v_lshl_add_u64 v[14:15], v[2:3], 0, s[18:19]
	s_mov_b32 m0, s8
	s_mov_b64 s[18:19], 0x16800
	v_readfirstlane_b32 s8, v17
	v_add_u32_e32 v17, 0x6000, v232
	global_load_lds_dwordx4 v[14:15], off
	v_lshl_add_u64 v[14:15], v[2:3], 0, s[18:19]
	s_mov_b32 m0, s8
	s_mov_b64 s[18:19], 0x2c800
	v_readfirstlane_b32 s8, v17
	global_load_lds_dwordx4 v[14:15], off
	v_lshl_add_u64 v[14:15], v[2:3], 0, s[18:19]
	s_mov_b32 m0, s8
	s_mov_b64 s[18:19], 0x42800
	global_load_lds_dwordx4 v[14:15], off
	v_add_u32_e32 v14, 0x7000, v232
	v_lshl_add_u64 v[2:3], v[2:3], 0, s[18:19]
	v_readfirstlane_b32 s8, v14
	s_mov_b32 m0, s8
	v_mul_f32_e32 v14, 0x4f800000, v20
	global_load_lds_dwordx4 v[2:3], off
	v_cmp_gt_f32_e32 vcc, s52, v20
	s_movk_i32 s8, 0x118
	v_bfe_u32 v16, v214, 1, 3
	v_cndmask_b32_e32 v14, v20, v14, vcc
	v_sqrt_f32_e32 v15, v14
	v_mul_f32_e32 v233, 0xbfb8aa3b, v1
	v_lshrrev_b32_e32 v1, 3, v8
	v_mov_b32_e32 v8, v0
	v_add_u32_e32 v2, -1, v15
	v_fma_f32 v3, -v2, v15, v14
	v_cmp_ge_f32_e64 s[40:41], 0, v3
	v_add_u32_e32 v3, 1, v15
	v_mov_b32_e32 v17, v0
	v_cndmask_b32_e64 v2, v15, v2, s[40:41]
	v_fma_f32 v15, -v3, v15, v14
	v_cmp_lt_f32_e64 s[40:41], 0, v15
	v_mov_b32_e32 v15, v0
	v_mov_b32_e32 v18, v0
	v_cndmask_b32_e64 v2, v2, v3, s[40:41]
	v_mul_f32_e32 v3, 0x37800000, v2
	v_cndmask_b32_e32 v2, v2, v3, vcc
	v_and_or_b32 v3, v10, s8, v11
	s_cselect_b32 s8, 0, 0
	s_addk_i32 s8, 0x4000
	v_add3_u32 v234, v13, s8, v3
	v_bitop3_b32 v3, v227, v9, 7 bitop3:0x78
	v_lshlrev_b32_e32 v239, 4, v3
	v_bitop3_b32 v3, v227, v16, 2 bitop3:0x36
	s_movk_i32 s8, 0x5800
	v_cmp_class_f32_e32 vcc, v14, v21
	v_lshlrev_b32_e32 v238, 4, v3
	v_bitop3_b32 v3, v227, v16, 4 bitop3:0x36
	v_mul_lo_u32 v1, v1, s8
	v_cndmask_b32_e32 v2, v2, v14, vcc
	v_lshlrev_b32_e32 v237, 4, v3
	v_bitop3_b32 v3, v227, v16, 6 bitop3:0x36
	v_mad_u32_u24 v1, v6, s33, v1
	s_add_u32 s18, s81, s7
	v_lshlrev_b32_e32 v235, 4, v3
	v_mul_f32_e32 v231, 0xbfb8aa3b, v2
	v_or3_b32 v2, v1, v7, v12
	v_mov_b32_e32 v3, v201
	s_addc_u32 s19, s82, s3
	v_lshl_add_u64 v[206:207], v[2:3], 1, s[18:19]
	v_lshl_add_u64 v[208:209], s[18:19], 0, v[4:5]
	s_mov_b64 s[40:41], 0
	v_mov_b32_e32 v1, v0
	v_mov_b32_e32 v2, v0
	v_mov_b32_e32 v3, v0
	v_mov_b32_e32 v4, v0
	v_mov_b32_e32 v5, v0
	v_mov_b32_e32 v6, v0
	v_mov_b32_e32 v7, v0
	v_mov_b32_e32 v9, v0
	v_mov_b32_e32 v10, v0
	v_mov_b32_e32 v11, v0
	v_mov_b32_e32 v12, v0
	v_mov_b32_e32 v13, v0
	v_mov_b32_e32 v14, v0
	v_mov_b32_e32 v16, v0
	v_mov_b32_e32 v19, v0
	v_mov_b32_e32 v20, v0
	v_mov_b32_e32 v21, v0
	v_mov_b32_e32 v24, v0
	v_mov_b32_e32 v25, v0
	v_mov_b32_e32 v26, v0
	v_mov_b32_e32 v27, v0
	v_mov_b32_e32 v28, v0
	v_mov_b32_e32 v29, v0
	v_mov_b32_e32 v30, v0
	v_mov_b32_e32 v31, v0
	v_mov_b32_e32 v32, v0
	v_mov_b32_e32 v33, v0
	v_mov_b32_e32 v34, v0
	v_mov_b32_e32 v35, v0
	v_mov_b32_e32 v36, v0
	v_mov_b32_e32 v37, v0
	v_mov_b32_e32 v38, v0
	v_mov_b32_e32 v39, v0
	v_mov_b32_e32 v40, v0
	v_mov_b32_e32 v41, v0
	v_mov_b32_e32 v42, v0
	v_mov_b32_e32 v43, v0
	v_mov_b32_e32 v44, v0
	v_mov_b32_e32 v45, v0
	v_mov_b32_e32 v46, v0
	v_mov_b32_e32 v47, v0
	v_mov_b32_e32 v48, v0
	v_mov_b32_e32 v49, v0
	v_mov_b32_e32 v50, v0
	v_mov_b32_e32 v51, v0
	v_mov_b32_e32 v52, v0
	v_mov_b32_e32 v53, v0
	v_mov_b32_e32 v54, v0
	v_mov_b32_e32 v55, v0
	v_mov_b32_e32 v56, v0
	v_mov_b32_e32 v57, v0
	v_mov_b32_e32 v58, v0
	v_mov_b32_e32 v59, v0
	v_mov_b32_e32 v60, v0
	v_mov_b32_e32 v61, v0
	v_mov_b32_e32 v62, v0
	v_mov_b32_e32 v63, v0
	v_mov_b32_e32 v64, v0
	v_mov_b32_e32 v65, v0
	v_mov_b32_e32 v66, v0
	v_mov_b32_e32 v67, v0
	v_mov_b32_e32 v68, v0
	v_mov_b32_e32 v69, v0
	v_mov_b32_e32 v70, v0
	v_mov_b32_e32 v71, v0
	v_mov_b32_e32 v72, v0
	v_mov_b32_e32 v73, v0
	v_mov_b32_e32 v74, v0
	v_mov_b32_e32 v75, v0
	v_mov_b32_e32 v76, v0
	v_mov_b32_e32 v77, v0
	v_mov_b32_e32 v78, v0
	v_mov_b32_e32 v79, v0
	v_mov_b32_e32 v80, v0
	v_mov_b32_e32 v81, v0
	v_mov_b32_e32 v82, v0
	v_mov_b32_e32 v83, v0
	v_mov_b32_e32 v84, v0
	v_mov_b32_e32 v85, v0
	v_mov_b32_e32 v86, v0
	v_mov_b32_e32 v87, v0
	v_mov_b32_e32 v88, v0
	v_mov_b32_e32 v89, v0
	v_mov_b32_e32 v90, v0
	v_mov_b32_e32 v91, v0
	v_mov_b32_e32 v92, v0
	v_mov_b32_e32 v93, v0
	v_mov_b32_e32 v94, v0
	v_mov_b32_e32 v95, v0
	v_mov_b32_e32 v96, v0
	v_mov_b32_e32 v97, v0
	v_mov_b32_e32 v98, v0
	v_mov_b32_e32 v99, v0
	v_mov_b32_e32 v100, v0
	v_mov_b32_e32 v101, v0
	v_mov_b32_e32 v102, v0
	v_mov_b32_e32 v103, v0
	v_mov_b32_e32 v104, v0
	v_mov_b32_e32 v105, v0
	v_mov_b32_e32 v106, v0
	v_mov_b32_e32 v107, v0
	v_mov_b32_e32 v108, v0
	v_mov_b32_e32 v109, v0
	v_mov_b32_e32 v110, v0
	v_mov_b32_e32 v111, v0
	v_mov_b32_e32 v112, v0
	v_mov_b32_e32 v113, v0
	v_mov_b32_e32 v114, v0
	v_mov_b32_e32 v115, v0
	v_mov_b32_e32 v116, v0
	v_mov_b32_e32 v117, v0
	v_mov_b32_e32 v118, v0
	v_mov_b32_e32 v119, v0
	v_mov_b32_e32 v120, v0
	v_mov_b32_e32 v121, v0
	v_mov_b32_e32 v122, v0
	v_mov_b32_e32 v123, v0
	v_mov_b32_e32 v124, v0
	v_mov_b32_e32 v125, v0
	v_mov_b32_e32 v126, v0
	v_mov_b32_e32 v127, v0
	v_mov_b32_e32 v204, v0
	v_mov_b32_e32 v205, v0
	v_add_u32_e32 v239, v236, v239
	v_add_u32_e32 v238, v236, v238
	v_add_u32_e32 v237, v236, v237
	v_add_u32_e32 v235, v236, v235
	v_readfirstlane_b32 s7, v232
	v_readfirstlane_b32 s40, v208
	v_readfirstlane_b32 s41, v209
	v_readfirstlane_b32 s98, v206
	v_readfirstlane_b32 s99, v207
	s_nop 3
	s_sub_u32 s40, s40, 0x1000
	s_subb_u32 s41, s41, 0
	s_sub_u32 s98, s98, 0x1000
	s_subb_u32 s99, s99, 0
	s_nop 1
	v_subrev_u32_e32 v248, s40, v208
	v_subrev_u32_e32 v249, s98, v206
	s_add_u32 s40, s40, 0xa128300
	s_addc_u32 s41, s41, 0
	s_add_u32 s98, s98, 0xa128700
	s_addc_u32 s99, s99, 0
	s_movk_i32 s6, 64
	s_and_b32 s18, s13, 32
	s_cmp_eq_u32 s18, 0
	s_cbranch_scc1 .Lattn_older
	s_setprio 1
	s_branch .Lattn_noprio
.Lattn_older:
	s_setprio 0

; #define SBAR() __builtin_amdgcn_sched_barrier(0)
; #define MFMA(a, b, c) __builtin_amdgcn_mfma_f32_32x32x16_bf16(a, b, c, 0, 0, 0)
; template <int D0> __device__ __forceinline__ void pv_two(f32x16& oa, f32x16& ob, int vb, bf16x8 a0, bf16x8 a1, bf16x8 a2, bf16x8 a3,
;                                                          bf16x8 b0, bf16x8 b1, bf16x8 b2, bf16x8 b3) {
;     ...
;   { const s16x4 l0 = tr_read<v_rd_off(D0, 0, 0)>(vb), h0 = tr_read<v_rd_off(D0, 0, 1)>(vb), l1 = tr_read<v_rd_off(D0, 1, 0)>(vb), h1 = tr_read<v_rd_off(D0, 1, 1)>(vb);
;     asm volatile("s_waitcnt lgkmcnt(0)" ::: "memory"); SBAR();
;     const bf16x8 v0 = PKV(l0, h0), v1 = PKV(l1, h1);
;     oa = MFMA(a0, v0, oa); ob = MFMA(b0, v0, ob); oa = MFMA(a1, v1, oa); ob = MFMA(b1, v1, ob); }
;   { const s16x4 l2 = tr_read<v_rd_off(D0, 2, 0)>(vb), h2 = tr_read<v_rd_off(D0, 2, 1)>(vb), l3 = tr_read<v_rd_off(D0, 3, 0)>(vb), h3 = tr_read<v_rd_off(D0, 3, 1)>(vb);
;     asm volatile("s_waitcnt lgkmcnt(0)" ::: "memory"); SBAR();
;     const bf16x8 v2 = PKV(l2, h2), v3 = PKV(l3, h3);
;     oa = MFMA(a2, v2, oa); ob = MFMA(b2, v2, ob); oa = MFMA(a3, v3, oa); ob = MFMA(b3, v3, ob); }
;     ...
; }
; __device__ __forceinline__ void sm_fixed(f32x16& p0, f32x16& p1, float mC, float& l_reg, bf16x8& pa0, bf16x8& pa1, bf16x8& pa2, bf16x8& pa3) {
;     ...
;   { auto rr = __builtin_amdgcn_permlane32_swap(__float_as_uint(ps), __float_as_uint(ps), false, false);
;     ps = __uint_as_float(rr[0]) + __uint_as_float(rr[1]); }
;   l_reg += ps;
.Lattn_exit:
	s_waitcnt lgkmcnt(6)
	v_mfma_f32_32x32x16_bf16 v[0:15], v[184:187], v[240:243], v[0:15]
	ds_read_b64_tr_b16 v[240:241], v234 offset:4096
	ds_read_b64_tr_b16 v[242:243], v234 offset:6144
	v_fmamk_f32 v144, v144, 0x3fb8aa3b, v231
	v_fmamk_f32 v145, v145, 0x3fb8aa3b, v231
	v_exp_f32_e32 v144, v144
	v_exp_f32_e32 v145, v145
	v_add_f32_e32 v205, v205, v144
	v_add_f32_e32 v205, v205, v145
	v_cvt_pk_bf16_f32 v192, v144, v145
	s_waitcnt lgkmcnt(6)
	v_mfma_f32_32x32x16_bf16 v[16:31], v[184:187], v[244:247], v[16:31]
	ds_read_b64_tr_b16 v[244:245], v234 offset:4608
	ds_read_b64_tr_b16 v[246:247], v234 offset:6656
	v_fmamk_f32 v146, v146, 0x3fb8aa3b, v231
	v_fmamk_f32 v147, v147, 0x3fb8aa3b, v231
	v_exp_f32_e32 v146, v146
	v_exp_f32_e32 v147, v147
	v_add_f32_e32 v205, v205, v146
	v_add_f32_e32 v205, v205, v147
	v_cvt_pk_bf16_f32 v193, v146, v147
	s_waitcnt lgkmcnt(6)
	v_mfma_f32_32x32x16_bf16 v[32:47], v[184:187], v[218:221], v[32:47]
	ds_read_b64_tr_b16 v[218:219], v234 offset:5120
	ds_read_b64_tr_b16 v[220:221], v234 offset:7168
	v_fmamk_f32 v148, v148, 0x3fb8aa3b, v231
	v_fmamk_f32 v149, v149, 0x3fb8aa3b, v231
	v_exp_f32_e32 v148, v148
	v_exp_f32_e32 v149, v149
	v_add_f32_e32 v205, v205, v148
	v_add_f32_e32 v205, v205, v149
	v_cvt_pk_bf16_f32 v194, v148, v149
	s_waitcnt lgkmcnt(6)
	v_mfma_f32_32x32x16_bf16 v[48:63], v[184:187], v[210:213], v[48:63]
	ds_read_b64_tr_b16 v[210:211], v234 offset:5632
	ds_read_b64_tr_b16 v[212:213], v234 offset:7680
	v_fmamk_f32 v150, v150, 0x3fb8aa3b, v231
	v_fmamk_f32 v151, v151, 0x3fb8aa3b, v231
	v_exp_f32_e32 v150, v150
	v_exp_f32_e32 v151, v151
	v_add_f32_e32 v205, v205, v150
	v_add_f32_e32 v205, v205, v151
	v_cvt_pk_bf16_f32 v195, v150, v151
	s_waitcnt lgkmcnt(6)
	v_mfma_f32_32x32x16_bf16 v[0:15], v[188:191], v[240:243], v[0:15]
	ds_read_b64_tr_b16 v[240:241], v234 offset:8192
	ds_read_b64_tr_b16 v[242:243], v234 offset:10240
	v_fmamk_f32 v152, v152, 0x3fb8aa3b, v231
	v_fmamk_f32 v153, v153, 0x3fb8aa3b, v231
	v_exp_f32_e32 v152, v152
	v_exp_f32_e32 v153, v153
	v_add_f32_e32 v205, v205, v152
	v_add_f32_e32 v205, v205, v153
	v_cvt_pk_bf16_f32 v196, v152, v153
	s_waitcnt lgkmcnt(6)
	v_mfma_f32_32x32x16_bf16 v[16:31], v[188:191], v[244:247], v[16:31]
	ds_read_b64_tr_b16 v[244:245], v234 offset:8704
	ds_read_b64_tr_b16 v[246:247], v234 offset:10752
	v_fmamk_f32 v154, v154, 0x3fb8aa3b, v231
	v_fmamk_f32 v155, v155, 0x3fb8aa3b, v231
	v_exp_f32_e32 v154, v154
	v_exp_f32_e32 v155, v155
	v_add_f32_e32 v205, v205, v154
	v_add_f32_e32 v205, v205, v155
	v_cvt_pk_bf16_f32 v197, v154, v155
	s_waitcnt lgkmcnt(6)
	v_mfma_f32_32x32x16_bf16 v[32:47], v[188:191], v[218:221], v[32:47]
	ds_read_b64_tr_b16 v[218:219], v234 offset:9216
	ds_read_b64_tr_b16 v[220:221], v234 offset:11264
	v_fmamk_f32 v156, v156, 0x3fb8aa3b, v231
	v_fmamk_f32 v157, v157, 0x3fb8aa3b, v231
	v_exp_f32_e32 v156, v156
	v_exp_f32_e32 v157, v157
	v_add_f32_e32 v205, v205, v156
	v_add_f32_e32 v205, v205, v157
	v_cvt_pk_bf16_f32 v198, v156, v157
	s_waitcnt lgkmcnt(6)
	v_mfma_f32_32x32x16_bf16 v[48:63], v[188:191], v[210:213], v[48:63]
	ds_read_b64_tr_b16 v[210:211], v234 offset:9728
	ds_read_b64_tr_b16 v[212:213], v234 offset:11776
	v_fmamk_f32 v158, v158, 0x3fb8aa3b, v231
	v_fmamk_f32 v159, v159, 0x3fb8aa3b, v231
	v_exp_f32_e32 v158, v158
	v_exp_f32_e32 v159, v159
	v_add_f32_e32 v205, v205, v158
	v_add_f32_e32 v205, v205, v159
	v_cvt_pk_bf16_f32 v199, v158, v159
	s_waitcnt lgkmcnt(6)
	v_mfma_f32_32x32x16_bf16 v[0:15], v[192:195], v[240:243], v[0:15]
	ds_read_b64_tr_b16 v[240:241], v234 offset:12288
	ds_read_b64_tr_b16 v[242:243], v234 offset:14336
	s_waitcnt lgkmcnt(6)
	v_mfma_f32_32x32x16_bf16 v[16:31], v[192:195], v[244:247], v[16:31]
	ds_read_b64_tr_b16 v[244:245], v234 offset:12800
	ds_read_b64_tr_b16 v[246:247], v234 offset:14848
	s_waitcnt lgkmcnt(6)
	v_mfma_f32_32x32x16_bf16 v[32:47], v[192:195], v[218:221], v[32:47]
	ds_read_b64_tr_b16 v[218:219], v234 offset:13312
	ds_read_b64_tr_b16 v[220:221], v234 offset:15360
	s_waitcnt lgkmcnt(6)
	v_mfma_f32_32x32x16_bf16 v[48:63], v[192:195], v[210:213], v[48:63]
	ds_read_b64_tr_b16 v[210:211], v234 offset:13824
	ds_read_b64_tr_b16 v[212:213], v234 offset:15872
	s_waitcnt lgkmcnt(6)
	v_mfma_f32_32x32x16_bf16 v[0:15], v[196:199], v[240:243], v[0:15]
	s_waitcnt lgkmcnt(4)
	v_mfma_f32_32x32x16_bf16 v[16:31], v[196:199], v[244:247], v[16:31]
	s_waitcnt lgkmcnt(2)
	v_mfma_f32_32x32x16_bf16 v[32:47], v[196:199], v[218:221], v[32:47]
	s_waitcnt lgkmcnt(0)
	v_mfma_f32_32x32x16_bf16 v[48:63], v[196:199], v[210:213], v[48:63]
	v_sub_u32_e32 v239, v239, v236
	v_sub_u32_e32 v238, v238, v236
	v_sub_u32_e32 v237, v237, v236
	v_sub_u32_e32 v235, v235, v236
	v_mov_b32_e32 v210, v204
	v_mov_b32_e32 v212, v204
	v_mov_b32_e32 v211, v205
	v_mov_b32_e32 v213, v205
	s_nop 1
	v_permlane32_swap_b32_e32 v210, v212
	v_permlane32_swap_b32_e32 v211, v213
	s_nop 1
	v_add_f32_e32 v204, v210, v212
	v_add_f32_e32 v205, v211, v213
	s_setprio 0
	s_and_b32 s18, s13, 32
	s_cmp_eq_u32 s18, 0
	s_cbranch_scc0 .Lattn_pdone
	s_setprio 1
; #define MFMA(a, b, c) __builtin_amdgcn_mfma_f32_32x32x16_bf16(a, b, c, 0, 0, 0)
; #define PK4N(PV, BASE, OUT) do { u32x4 w_ = {cvtpk(PV[BASE + 0], PV[BASE + 1]), cvtpk(PV[BASE + 2], PV[BASE + 3]), \
;     cvtpk(PV[BASE + 4], PV[BASE + 5]), cvtpk(PV[BASE + 6], PV[BASE + 7])}; OUT = *reinterpret_cast<bf16x8*>(&w_); } while (0)
; __device__ __forceinline__ void att_qkt(f32x16& p0, f32x16& p1, const char* Kb, const bf16x8 (&qr)[4], int koff, int ksw, int hi) {
;   p0 = f32x16{}; p1 = f32x16{};
; #pragma unroll
;   for (int d0 = 0; d0 < 4; ++d0) {
;     const int co = ((d0 * 2 + hi) ^ ksw) << 4;
;     const bf16x8 b0 = *(const bf16x8*)(Kb + koff + co);
;     const bf16x8 b1 = *(const bf16x8*)(Kb + koff + 4096 + co);
;     p0 = MFMA(b0, qr[d0], p0); p1 = MFMA(b1, qr[d0], p1);
;   }
; }
; __device__ __forceinline__ void sm_fixed(f32x16& p0, f32x16& p1, float mC, float& l_reg, bf16x8& pa0, bf16x8& pa1, bf16x8& pa2, bf16x8& pa3) {
;   constexpr float C = 1.4426950408889634f;
; #pragma unroll
;   for (int r = 0; r < 16; ++r) p0[r] = __builtin_amdgcn_exp2f(fmaf(p0[r], C, -mC));
; #pragma unroll
;   for (int r = 0; r < 16; ++r) p1[r] = __builtin_amdgcn_exp2f(fmaf(p1[r], C, -mC));
;   float ps = 0;
; #pragma unroll
;   for (int r = 0; r < 16; ++r) ps += p0[r];
; #pragma unroll
;   for (int r = 0; r < 16; ++r) ps += p1[r];
;   { auto rr = __builtin_amdgcn_permlane32_swap(__float_as_uint(ps), __float_as_uint(ps), false, false);
;     ps = __uint_as_float(rr[0]) + __uint_as_float(rr[1]); }
;   l_reg += ps;
;     ...
;   PK4N(p0, 0, pa0); PK4N(p0, 8, pa1); PK4N(p1, 0, pa2); PK4N(p1, 8, pa3);
.Lattn_pdone:
	v_add_u32_e32 v198, v236, v239
	s_waitcnt vmcnt(0)
	s_waitcnt vmcnt(0)
	s_barrier
	ds_read_b128 v[128:131], v198 offset:32768
	ds_read_b128 v[132:135], v198 offset:36864
	v_add_u32_e32 v199, v236, v238
	s_waitcnt lgkmcnt(1)
	v_mfma_f32_32x32x16_bf16 v[144:159], v[128:131], v[180:183], 0
	v_add_u32_e32 v206, v236, v237
	ds_read_b128 v[186:189], v199 offset:36864
	v_add_u32_e32 v207, v236, v235
	v_and_b32_e32 v184, 0x3fffffc0, v214
	s_add_i32 s3, 0, 0x10000
	ds_read_b128 v[190:193], v206 offset:36864
	v_lshl_add_u32 v184, v184, 2, s3
	s_waitcnt lgkmcnt(2)
	v_mfma_f32_32x32x16_bf16 v[128:143], v[132:135], v[180:183], 0
	ds_read_b128 v[180:183], v199 offset:32768
	v_add_u32_e32 v185, 0x8000, v234
	ds_read_b128 v[194:197], v207 offset:36864
	s_waitcnt lgkmcnt(1)
	v_mfma_f32_32x32x16_bf16 v[144:159], v[180:183], v[176:179], v[144:159]
	ds_read_b128 v[180:183], v206 offset:32768
	s_waitcnt lgkmcnt(0)
	v_mfma_f32_32x32x16_bf16 v[144:159], v[180:183], v[172:175], v[144:159]
	ds_read_b128 v[180:183], v207 offset:32768
	v_mfma_f32_32x32x16_bf16 v[128:143], v[186:189], v[176:179], v[128:143]
	s_waitcnt lgkmcnt(0)
	v_mfma_f32_32x32x16_bf16 v[144:159], v[180:183], v[168:171], v[144:159]
	v_mfma_f32_32x32x16_bf16 v[128:143], v[190:193], v[172:175], v[128:143]
	s_nop 10
	v_fmamk_f32 v144, v144, 0x3fb8aa3b, v233
	v_fmamk_f32 v145, v145, 0x3fb8aa3b, v233
	v_exp_f32_e32 v144, v144
	v_fmamk_f32 v146, v146, 0x3fb8aa3b, v233
	v_exp_f32_e32 v145, v145
	v_fmamk_f32 v147, v147, 0x3fb8aa3b, v233
	v_exp_f32_e32 v146, v146
	v_fmamk_f32 v148, v148, 0x3fb8aa3b, v233
	v_exp_f32_e32 v147, v147
	v_fmamk_f32 v149, v149, 0x3fb8aa3b, v233
	v_exp_f32_e32 v148, v148
	v_mfma_f32_32x32x16_bf16 v[128:143], v[194:197], v[168:171], v[128:143]
	v_add_f32_e32 v168, 0, v144
	v_fmamk_f32 v150, v150, 0x3fb8aa3b, v233
	v_exp_f32_e32 v149, v149
	v_add_f32_e32 v168, v145, v168
	v_fmamk_f32 v151, v151, 0x3fb8aa3b, v233
	v_exp_f32_e32 v150, v150
	v_add_f32_e32 v168, v146, v168
	v_fmamk_f32 v152, v152, 0x3fb8aa3b, v233
	v_exp_f32_e32 v151, v151
	v_add_f32_e32 v168, v147, v168
	v_exp_f32_e32 v152, v152
	v_fmamk_f32 v153, v153, 0x3fb8aa3b, v233
	v_add_f32_e32 v168, v148, v168
	v_exp_f32_e32 v153, v153
	v_fmamk_f32 v154, v154, 0x3fb8aa3b, v233
	v_add_f32_e32 v168, v149, v168
	v_exp_f32_e32 v154, v154
	v_fmamk_f32 v155, v155, 0x3fb8aa3b, v233
	v_add_f32_e32 v168, v150, v168
	v_exp_f32_e32 v155, v155
	v_fmamk_f32 v156, v156, 0x3fb8aa3b, v233
	v_add_f32_e32 v168, v151, v168
	v_exp_f32_e32 v156, v156
	v_fmamk_f32 v157, v157, 0x3fb8aa3b, v233
	v_add_f32_e32 v168, v152, v168
	v_exp_f32_e32 v157, v157
	v_fmamk_f32 v158, v158, 0x3fb8aa3b, v233
	v_add_f32_e32 v168, v153, v168
	v_exp_f32_e32 v158, v158
	v_fmamk_f32 v159, v159, 0x3fb8aa3b, v233
	v_add_f32_e32 v168, v154, v168
	v_exp_f32_e32 v159, v159
	v_fmamk_f32 v128, v128, 0x3fb8aa3b, v233
	v_add_f32_e32 v168, v155, v168
	v_exp_f32_e32 v128, v128
	v_fmamk_f32 v129, v129, 0x3fb8aa3b, v233
	v_add_f32_e32 v168, v156, v168
	v_exp_f32_e32 v129, v129
	v_fmamk_f32 v130, v130, 0x3fb8aa3b, v233
	v_add_f32_e32 v168, v157, v168
	v_exp_f32_e32 v130, v130
	v_fmamk_f32 v131, v131, 0x3fb8aa3b, v233
	v_add_f32_e32 v168, v158, v168
	v_exp_f32_e32 v131, v131
	v_fmamk_f32 v132, v132, 0x3fb8aa3b, v233
	v_add_f32_e32 v168, v159, v168
	v_exp_f32_e32 v132, v132
	v_fmamk_f32 v133, v133, 0x3fb8aa3b, v233
	v_add_f32_e32 v168, v128, v168
	v_exp_f32_e32 v133, v133
	v_fmamk_f32 v134, v134, 0x3fb8aa3b, v233
	v_add_f32_e32 v168, v129, v168
	v_exp_f32_e32 v134, v134
	v_fmamk_f32 v135, v135, 0x3fb8aa3b, v233
	v_add_f32_e32 v168, v130, v168
	v_exp_f32_e32 v135, v135
	v_fmamk_f32 v136, v136, 0x3fb8aa3b, v233
	v_add_f32_e32 v168, v131, v168
	v_exp_f32_e32 v136, v136
	v_fmamk_f32 v137, v137, 0x3fb8aa3b, v233
	v_add_f32_e32 v168, v132, v168
	v_exp_f32_e32 v137, v137
	v_fmamk_f32 v138, v138, 0x3fb8aa3b, v233
	v_add_f32_e32 v168, v133, v168
	v_exp_f32_e32 v138, v138
	v_fmamk_f32 v139, v139, 0x3fb8aa3b, v233
	v_add_f32_e32 v168, v134, v168
	v_exp_f32_e32 v139, v139
	v_fmamk_f32 v140, v140, 0x3fb8aa3b, v233
	v_add_f32_e32 v168, v135, v168
	v_exp_f32_e32 v140, v140
	v_fmamk_f32 v141, v141, 0x3fb8aa3b, v233
	v_add_f32_e32 v168, v136, v168
	v_exp_f32_e32 v141, v141
	v_fmamk_f32 v142, v142, 0x3fb8aa3b, v233
	v_add_f32_e32 v168, v137, v168
	v_exp_f32_e32 v142, v142
	v_fmac_f32_e32 v233, 0x3fb8aa3b, v143
	v_add_f32_e32 v168, v138, v168
	v_exp_f32_e32 v143, v233
	v_add_f32_e32 v168, v139, v168
	v_add_f32_e32 v168, v140, v168
	v_add_f32_e32 v168, v141, v168
	v_add_f32_e32 v168, v142, v168
	v_add_f32_e32 v186, v143, v168
	v_mov_b32_e32 v187, v186
	s_nop 1
	v_permlane32_swap_b32_e32 v186, v187
	v_cvt_pk_bf16_f32 v176, v144, v145
	v_cvt_pk_bf16_f32 v177, v146, v147
	v_cvt_pk_bf16_f32 v178, v148, v149
	v_cvt_pk_bf16_f32 v179, v150, v151
	v_cvt_pk_bf16_f32 v180, v152, v153
	v_cvt_pk_bf16_f32 v181, v154, v155
	v_cvt_pk_bf16_f32 v182, v156, v157
	v_cvt_pk_bf16_f32 v183, v158, v159
	v_cvt_pk_bf16_f32 v168, v128, v129
	v_cvt_pk_bf16_f32 v169, v130, v131
	v_cvt_pk_bf16_f32 v170, v132, v133
	v_cvt_pk_bf16_f32 v171, v134, v135
	v_cvt_pk_bf16_f32 v172, v136, v137
	v_cvt_pk_bf16_f32 v173, v138, v139
	v_cvt_pk_bf16_f32 v174, v140, v141
	v_cvt_pk_bf16_f32 v175, v142, v143
	ds_read_b128 v[128:131], v198 offset:40960
	ds_read_b128 v[132:135], v198 offset:45056
	s_waitcnt lgkmcnt(1)
	v_mfma_f32_32x32x16_bf16 v[144:159], v[128:131], v[164:167], 0
	s_waitcnt lgkmcnt(0)
	v_mfma_f32_32x32x16_bf16 v[128:143], v[132:135], v[164:167], 0
	ds_read_b128 v[164:167], v199 offset:40960
	ds_read_b128 v[188:191], v199 offset:45056
	s_waitcnt lgkmcnt(0)
; #define MFMA(a, b, c) __builtin_amdgcn_mfma_f32_32x32x16_bf16(a, b, c, 0, 0, 0)
; #define PK4N(PV, BASE, OUT) do { u32x4 w_ = {cvtpk(PV[BASE + 0], PV[BASE + 1]), cvtpk(PV[BASE + 2], PV[BASE + 3]), \
;     cvtpk(PV[BASE + 4], PV[BASE + 5]), cvtpk(PV[BASE + 6], PV[BASE + 7])}; OUT = *reinterpret_cast<bf16x8*>(&w_); } while (0)
; __device__ __forceinline__ void sm_fixed(f32x16& p0, f32x16& p1, float mC, float& l_reg, bf16x8& pa0, bf16x8& pa1, bf16x8& pa2, bf16x8& pa3) {
;   constexpr float C = 1.4426950408889634f;
; #pragma unroll
;   for (int r = 0; r < 16; ++r) p0[r] = __builtin_amdgcn_exp2f(fmaf(p0[r], C, -mC));
; #pragma unroll
;   for (int r = 0; r < 16; ++r) p1[r] = __builtin_amdgcn_exp2f(fmaf(p1[r], C, -mC));
;   float ps = 0;
; #pragma unroll
;   for (int r = 0; r < 16; ++r) ps += p0[r];
; #pragma unroll
;   for (int r = 0; r < 16; ++r) ps += p1[r];
;   { auto rr = __builtin_amdgcn_permlane32_swap(__float_as_uint(ps), __float_as_uint(ps), false, false);
;     ps = __uint_as_float(rr[0]) + __uint_as_float(rr[1]); }
;   l_reg += ps;
;     ...
;   PK4N(p0, 0, pa0); PK4N(p0, 8, pa1); PK4N(p1, 0, pa2); PK4N(p1, 8, pa3);
; __device__ __forceinline__ void att_qkt_p(f32x16& p0, f32x16& p1, const char* Kb, const bf16x8 (&qr)[2], const char* Qp, int koff, int ksw, int hi) {
;   p0 = f32x16{}; p1 = f32x16{};
; #pragma unroll
;   for (int d0 = 0; d0 < 4; ++d0) {
;     const int co = ((d0 * 2 + hi) ^ ksw) << 4;
;     const bf16x8 b0 = *(const bf16x8*)(Kb + koff + co);
;     const bf16x8 b1 = *(const bf16x8*)(Kb + koff + 4096 + co);
;     const bf16x8 qd = d0 < 2 ? qr[d0 & 1] : *(const bf16x8*)(Qp + (d0 - 2) * 4096);
;     p0 = MFMA(b0, qd, p0); p1 = MFMA(b1, qd, p1);
;   }
; }
	v_mfma_f32_32x32x16_bf16 v[128:143], v[188:191], v[160:163], v[128:143]
	v_mfma_f32_32x32x16_bf16 v[144:159], v[164:167], v[160:163], v[144:159]
	ds_read_b128 v[160:163], v206 offset:40960
	ds_read_b128 v[164:167], v206 offset:45056
	ds_read_b128 v[188:191], v230
	s_waitcnt lgkmcnt(0)
	v_mfma_f32_32x32x16_bf16 v[128:143], v[164:167], v[188:191], v[128:143]
	v_mfma_f32_32x32x16_bf16 v[144:159], v[160:163], v[188:191], v[144:159]
	ds_read_b128 v[160:163], v207 offset:40960
	ds_read_b128 v[164:167], v207 offset:45056
	ds_read_b128 v[188:191], v230 offset:4096
	s_waitcnt lgkmcnt(0)
	v_mfma_f32_32x32x16_bf16 v[128:143], v[164:167], v[188:191], v[128:143]
	v_mfma_f32_32x32x16_bf16 v[144:159], v[160:163], v[188:191], v[144:159]
	s_nop 10
	v_fmamk_f32 v128, v128, 0x3fb8aa3b, v231
	v_exp_f32_e32 v162, v128
	v_fmamk_f32 v128, v129, 0x3fb8aa3b, v231
	v_exp_f32_e32 v163, v128
	v_fmamk_f32 v128, v130, 0x3fb8aa3b, v231
	v_exp_f32_e32 v164, v128
	v_fmamk_f32 v128, v131, 0x3fb8aa3b, v231
	v_exp_f32_e32 v165, v128
	v_fmamk_f32 v128, v132, 0x3fb8aa3b, v231
	v_exp_f32_e32 v166, v128
	v_fmamk_f32 v128, v133, 0x3fb8aa3b, v231
	v_exp_f32_e32 v167, v128
	v_fmamk_f32 v128, v134, 0x3fb8aa3b, v231
	v_exp_f32_e32 v188, v128
	v_fmamk_f32 v128, v135, 0x3fb8aa3b, v231
	v_exp_f32_e32 v189, v128
	v_fmamk_f32 v128, v136, 0x3fb8aa3b, v231
	v_exp_f32_e32 v190, v128
	v_fmamk_f32 v128, v137, 0x3fb8aa3b, v231
	v_fmamk_f32 v144, v144, 0x3fb8aa3b, v231
	v_exp_f32_e32 v191, v128
	v_fmamk_f32 v128, v138, 0x3fb8aa3b, v231
	v_exp_f32_e32 v160, v144
	v_fmamk_f32 v144, v145, 0x3fb8aa3b, v231
	v_exp_f32_e32 v192, v128
	v_fmamk_f32 v128, v139, 0x3fb8aa3b, v231
	v_exp_f32_e32 v145, v144
	v_fmamk_f32 v144, v146, 0x3fb8aa3b, v231
	v_exp_f32_e32 v193, v128
	v_fmamk_f32 v128, v140, 0x3fb8aa3b, v231
	v_exp_f32_e32 v161, v144
	v_fmamk_f32 v144, v147, 0x3fb8aa3b, v231
	v_exp_f32_e32 v194, v128
	v_fmamk_f32 v128, v141, 0x3fb8aa3b, v231
	v_exp_f32_e32 v147, v144
	v_fmamk_f32 v144, v148, 0x3fb8aa3b, v231
	v_exp_f32_e32 v195, v128
	v_fmamk_f32 v128, v142, 0x3fb8aa3b, v231
	v_exp_f32_e32 v148, v144
	v_fmamk_f32 v144, v149, 0x3fb8aa3b, v231
	v_exp_f32_e32 v196, v128
	v_add_f32_e32 v128, 0, v160
	v_exp_f32_e32 v149, v144
	v_fmamk_f32 v144, v150, 0x3fb8aa3b, v231
	v_add_f32_e32 v128, v145, v128
	v_exp_f32_e32 v150, v144
	v_fmamk_f32 v144, v151, 0x3fb8aa3b, v231
	v_add_f32_e32 v128, v161, v128
	v_exp_f32_e32 v151, v144
	v_fmamk_f32 v144, v152, 0x3fb8aa3b, v231
	v_add_f32_e32 v128, v147, v128
	v_exp_f32_e32 v152, v144
	v_fmamk_f32 v144, v153, 0x3fb8aa3b, v231
	v_add_f32_e32 v128, v148, v128
	v_exp_f32_e32 v153, v144
	v_fmamk_f32 v144, v154, 0x3fb8aa3b, v231
	v_add_f32_e32 v128, v149, v128
	v_exp_f32_e32 v154, v144
	v_fmamk_f32 v144, v155, 0x3fb8aa3b, v231
	v_add_f32_e32 v128, v150, v128
	v_exp_f32_e32 v155, v144
	v_fmamk_f32 v144, v156, 0x3fb8aa3b, v231
	v_add_f32_e32 v128, v151, v128
	v_exp_f32_e32 v156, v144
	v_fmamk_f32 v144, v157, 0x3fb8aa3b, v231
	v_add_f32_e32 v128, v152, v128
	v_exp_f32_e32 v157, v144
	v_fmamk_f32 v144, v158, 0x3fb8aa3b, v231
	v_add_f32_e32 v128, v153, v128
	v_exp_f32_e32 v158, v144
	v_fmamk_f32 v144, v159, 0x3fb8aa3b, v231
	v_add_f32_e32 v128, v154, v128
	v_exp_f32_e32 v159, v144
	v_add_f32_e32 v128, v155, v128
	v_add_f32_e32 v128, v156, v128
	v_add_f32_e32 v128, v157, v128
	v_add_f32_e32 v128, v158, v128
	v_add_f32_e32 v128, v159, v128
	v_add_f32_e32 v128, v162, v128
	v_add_f32_e32 v128, v163, v128
	v_add_f32_e32 v128, v164, v128
	v_add_f32_e32 v128, v165, v128
	v_add_f32_e32 v128, v166, v128
	v_add_f32_e32 v128, v167, v128
	v_add_f32_e32 v128, v188, v128
	v_add_f32_e32 v128, v189, v128
	v_add_f32_e32 v128, v190, v128
	v_add_f32_e32 v128, v191, v128
	v_fmac_f32_e32 v231, 0x3fb8aa3b, v143
	v_add_f32_e32 v128, v192, v128
	v_exp_f32_e32 v143, v231
	v_add_f32_e32 v128, v193, v128
	v_add_f32_e32 v128, v194, v128
	v_add_f32_e32 v128, v195, v128
	v_add_f32_e32 v128, v196, v128
	v_add_f32_e32 v144, v143, v128
	v_mov_b32_e32 v146, v144
	s_nop 1
	v_permlane32_swap_b32_e32 v144, v146
	v_cvt_pk_bf16_f32 v128, v160, v145
	v_cvt_pk_bf16_f32 v129, v161, v147
	v_cvt_pk_bf16_f32 v130, v148, v149
	v_cvt_pk_bf16_f32 v131, v150, v151
	v_cvt_pk_bf16_f32 v132, v152, v153
	v_cvt_pk_bf16_f32 v133, v154, v155
	v_cvt_pk_bf16_f32 v134, v156, v157
	v_cvt_pk_bf16_f32 v135, v158, v159
	v_cvt_pk_bf16_f32 v136, v162, v163
	v_cvt_pk_bf16_f32 v137, v164, v165
	v_cvt_pk_bf16_f32 v138, v166, v167
	v_cvt_pk_bf16_f32 v139, v188, v189
	v_cvt_pk_bf16_f32 v140, v190, v191
	v_cvt_pk_bf16_f32 v141, v192, v193
	v_cvt_pk_bf16_f32 v142, v194, v195
	v_cvt_pk_bf16_f32 v143, v196, v143
	ds_read_b64_tr_b16 v[148:149], v185 offset:0
	ds_read_b64_tr_b16 v[150:151], v185 offset:0x800
	ds_read_b64_tr_b16 v[152:153], v185 offset:0x1000
	ds_read_b64_tr_b16 v[154:155], v185 offset:0x1800
	s_waitcnt lgkmcnt(0)
	s_nop 0
	v_mfma_f32_32x32x16_bf16 v[64:79], v[176:179], v[148:151], v[64:79]
	v_mfma_f32_32x32x16_bf16 v[0:15], v[128:131], v[148:151], v[0:15]
	ds_read_b64_tr_b16 v[148:149], v185 offset:0x2000
	ds_read_b64_tr_b16 v[150:151], v185 offset:0x2800
	v_mfma_f32_32x32x16_bf16 v[64:79], v[180:183], v[152:155], v[64:79]
	v_mfma_f32_32x32x16_bf16 v[0:15], v[132:135], v[152:155], v[0:15]
	ds_read_b64_tr_b16 v[152:153], v185 offset:0x3000
	ds_read_b64_tr_b16 v[154:155], v185 offset:0x3800
	s_waitcnt lgkmcnt(0)
; __device__ __forceinline__ int crow(int r, int hi) { return (r & 3) + 8 * (r >> 2) + 4 * hi; }
; #define SBAR() __builtin_amdgcn_sched_barrier(0)
; #define MFMA(a, b, c) __builtin_amdgcn_mfma_f32_32x32x16_bf16(a, b, c, 0, 0, 0)
; template <int D0> __device__ __forceinline__ void pv_two(f32x16& oa, f32x16& ob, int vb, bf16x8 a0, bf16x8 a1, bf16x8 a2, bf16x8 a3,
;                                                          bf16x8 b0, bf16x8 b1, bf16x8 b2, bf16x8 b3) {
;     ...
;   { const s16x4 l0 = tr_read<v_rd_off(D0, 0, 0)>(vb), h0 = tr_read<v_rd_off(D0, 0, 1)>(vb), l1 = tr_read<v_rd_off(D0, 1, 0)>(vb), h1 = tr_read<v_rd_off(D0, 1, 1)>(vb);
;     asm volatile("s_waitcnt lgkmcnt(0)" ::: "memory"); SBAR();
;     const bf16x8 v0 = PKV(l0, h0), v1 = PKV(l1, h1);
;     oa = MFMA(a0, v0, oa); ob = MFMA(b0, v0, ob); oa = MFMA(a1, v1, oa); ob = MFMA(b1, v1, ob); }
;   { const s16x4 l2 = tr_read<v_rd_off(D0, 2, 0)>(vb), h2 = tr_read<v_rd_off(D0, 2, 1)>(vb), l3 = tr_read<v_rd_off(D0, 3, 0)>(vb), h3 = tr_read<v_rd_off(D0, 3, 1)>(vb);
;     asm volatile("s_waitcnt lgkmcnt(0)" ::: "memory"); SBAR();
;     const bf16x8 v2 = PKV(l2, h2), v3 = PKV(l3, h3);
;     oa = MFMA(a2, v2, oa); ob = MFMA(b2, v2, ob); oa = MFMA(a3, v3, oa); ob = MFMA(b3, v3, ob); }
;     ...
; }
; __device__ __forceinline__ void attn_item(const P& p, int layer, int item, char* lds) {
;     ...
;   float r1[16], r2[16];
;   if (hi == 0) li_l[r32] = l1;
;   asm volatile("s_waitcnt lgkmcnt(0)" ::: "memory");
; #pragma unroll
;   for (int r = 0; r < 16; ++r) r1[r] = 1.f / li_l[crow(r, hi)];
;   asm volatile("s_waitcnt lgkmcnt(0)" ::: "memory");
;   if (hi == 0) li_l[r32] = l2;
	v_mfma_f32_32x32x16_bf16 v[64:79], v[168:171], v[148:151], v[64:79]
	v_mfma_f32_32x32x16_bf16 v[0:15], v[136:139], v[148:151], v[0:15]
	ds_read_b64_tr_b16 v[148:149], v185 offset:0x200
	ds_read_b64_tr_b16 v[150:151], v185 offset:0xa00
	v_mfma_f32_32x32x16_bf16 v[64:79], v[172:175], v[152:155], v[64:79]
	v_mfma_f32_32x32x16_bf16 v[0:15], v[140:143], v[152:155], v[0:15]
	ds_read_b64_tr_b16 v[152:153], v185 offset:0x1200
	ds_read_b64_tr_b16 v[154:155], v185 offset:0x1a00
	s_waitcnt lgkmcnt(0)
	v_mfma_f32_32x32x16_bf16 v[80:95], v[176:179], v[148:151], v[80:95]
	v_mfma_f32_32x32x16_bf16 v[16:31], v[128:131], v[148:151], v[16:31]
	ds_read_b64_tr_b16 v[148:149], v185 offset:0x2200
	ds_read_b64_tr_b16 v[150:151], v185 offset:0x2a00
	v_mfma_f32_32x32x16_bf16 v[80:95], v[180:183], v[152:155], v[80:95]
	v_mfma_f32_32x32x16_bf16 v[16:31], v[132:135], v[152:155], v[16:31]
	ds_read_b64_tr_b16 v[152:153], v185 offset:0x3200
	ds_read_b64_tr_b16 v[154:155], v185 offset:0x3a00
	s_waitcnt lgkmcnt(0)
	v_mfma_f32_32x32x16_bf16 v[80:95], v[168:171], v[148:151], v[80:95]
	v_mfma_f32_32x32x16_bf16 v[16:31], v[136:139], v[148:151], v[16:31]
	ds_read_b64_tr_b16 v[148:149], v185 offset:0x400
	ds_read_b64_tr_b16 v[150:151], v185 offset:0xc00
	v_mfma_f32_32x32x16_bf16 v[80:95], v[172:175], v[152:155], v[80:95]
	v_mfma_f32_32x32x16_bf16 v[16:31], v[140:143], v[152:155], v[16:31]
	ds_read_b64_tr_b16 v[152:153], v185 offset:0x1400
	ds_read_b64_tr_b16 v[154:155], v185 offset:0x1c00
	s_waitcnt lgkmcnt(0)
	v_mfma_f32_32x32x16_bf16 v[96:111], v[176:179], v[148:151], v[96:111]
	v_mfma_f32_32x32x16_bf16 v[32:47], v[128:131], v[148:151], v[32:47]
	ds_read_b64_tr_b16 v[148:149], v185 offset:0x2400
	ds_read_b64_tr_b16 v[150:151], v185 offset:0x2c00
	v_mfma_f32_32x32x16_bf16 v[96:111], v[180:183], v[152:155], v[96:111]
	v_mfma_f32_32x32x16_bf16 v[32:47], v[132:135], v[152:155], v[32:47]
	ds_read_b64_tr_b16 v[152:153], v185 offset:0x3400
	ds_read_b64_tr_b16 v[154:155], v185 offset:0x3c00
	s_waitcnt lgkmcnt(0)
	v_mfma_f32_32x32x16_bf16 v[96:111], v[168:171], v[148:151], v[96:111]
	v_mfma_f32_32x32x16_bf16 v[32:47], v[136:139], v[148:151], v[32:47]
	ds_read_b64_tr_b16 v[148:149], v185 offset:0x600
	ds_read_b64_tr_b16 v[150:151], v185 offset:0xe00
	v_mfma_f32_32x32x16_bf16 v[96:111], v[172:175], v[152:155], v[96:111]
	v_mfma_f32_32x32x16_bf16 v[32:47], v[140:143], v[152:155], v[32:47]
	ds_read_b64_tr_b16 v[152:153], v185 offset:0x1600
	ds_read_b64_tr_b16 v[154:155], v185 offset:0x1e00
	s_waitcnt lgkmcnt(0)
	v_mfma_f32_32x32x16_bf16 v[112:127], v[176:179], v[148:151], v[112:127]
	v_mfma_f32_32x32x16_bf16 v[48:63], v[128:131], v[148:151], v[48:63]
	ds_read_b64_tr_b16 v[128:129], v185 offset:0x2600
	ds_read_b64_tr_b16 v[130:131], v185 offset:0x2e00
	ds_read_b64_tr_b16 v[148:149], v185 offset:0x3600
	ds_read_b64_tr_b16 v[150:151], v185 offset:0x3e00
	s_waitcnt lgkmcnt(0)
	v_mfma_f32_32x32x16_bf16 v[112:127], v[180:183], v[152:155], v[112:127]
	v_mfma_f32_32x32x16_bf16 v[48:63], v[132:135], v[152:155], v[48:63]
	v_mfma_f32_32x32x16_bf16 v[112:127], v[168:171], v[128:131], v[112:127]
	v_cmp_gt_u32_e32 vcc, 32, v228
	v_lshl_add_u32 v147, v226, 2, v184
	v_mfma_f32_32x32x16_bf16 v[48:63], v[136:139], v[128:131], v[48:63]
	v_mfma_f32_32x32x16_bf16 v[112:127], v[172:175], v[148:151], v[112:127]
	v_mfma_f32_32x32x16_bf16 v[48:63], v[140:143], v[148:151], v[48:63]
	s_and_saveexec_b64 s[6:7], vcc
	v_add_f32_e32 v128, v186, v187
	v_add_f32_e32 v128, v204, v128
	ds_write_b32 v147, v128
	s_or_b64 exec, exec, s[6:7]
	s_waitcnt lgkmcnt(0)
	v_add_u32_e32 v145, v184, v200
	ds_read_b128 v[128:131], v145
	ds_read_b128 v[132:135], v145 offset:32
	ds_read_b128 v[136:139], v145 offset:64
	ds_read_b128 v[140:143], v145 offset:96
	s_waitcnt lgkmcnt(0)
	s_mov_b64 s[6:7], exec
	s_and_b64 s[18:19], s[6:7], vcc
	v_mov_b32_e32 v206, 0x14000
	v_mov_b32_e32 v207, 0x68000
	v_mov_b32_e32 v208, 0x16000
	v_mov_b32_e32 v209, 0x66000
	v_mov_b32_e32 v210, 0x18000
	v_mov_b32_e32 v211, 0x64000
	v_mov_b32_e32 v212, 0x1a000
	v_mov_b32_e32 v213, 0x62000
	v_mov_b32_e32 v214, 0x1c000
	v_mov_b32_e32 v216, 0x60000
	v_mov_b32_e32 v218, 0x1e000
	v_mov_b32_e32 v219, 0x5e000
	v_mov_b32_e32 v220, 0x20000
	v_mov_b32_e32 v221, 0x5c000
	v_mov_b32_e32 v228, 0x22000
	v_mov_b32_e32 v230, 0x5a000
	v_mov_b32_e32 v231, 0x24000
	v_mov_b32_e32 v232, 0x58000
	v_mov_b32_e32 v233, 0x26000
	v_mov_b32_e32 v234, 0x56000
	v_mov_b32_e32 v235, 0x28000
	v_mov_b32_e32 v236, 0x54000
	v_mov_b32_e32 v237, 0x2a000
	v_mov_b32_e32 v238, 0x52000
	v_mov_b32_e32 v239, 0x2c000
	v_mov_b32_e32 v240, 0x50000
	v_mov_b32_e32 v241, 0x2e000
	v_mov_b32_e32 v242, 0x4e000
	v_mov_b32_e32 v243, 0x30000
	v_mov_b32_e32 v244, 0x4c000
	v_mov_b32_e32 v245, 0x32000
	v_mov_b32_e32 v246, 0x4a000
	v_mov_b32_e32 v247, 0x34000
	v_mov_b32_e32 v248, 0x48000
	v_mov_b32_e32 v249, 0x36000
	v_mov_b32_e32 v179, 0x46000
	v_mov_b32_e32 v181, 0x38000
	s_mov_b64 exec, s[18:19]
	s_cbranch_execz .LBB0_270
	v_add_f32_e32 v144, v144, v146
	v_add_f32_e32 v144, v205, v144
	ds_write_b32 v147, v144
	s_branch .LBB0_270
